# final rmsnorm phase rebalanced: workgroups 0-127 take 3 prompt rows + the sample row per wave, workgroups 128-255 take 5 prompt rows
# baseline (speedup 1.0000x reference)
; __device__ __forceinline__ int opaque_tid() { int t = threadIdx.x; asm volatile("" : "+v"(t)); return t; }
; __device__ __forceinline__ int opaque_bid() { int t = blockIdx.x; asm volatile("" : "+s"(t)); return t; }
; __device__ __forceinline__ void phase_final(const Params& p) {
;     const int tid = opaque_tid(), wid = tid >> 6, lane = tid & 63;
;     const float* SS3 = (const float*)(p.ws + WS_SS3); const float* nw = p.in[26];
;     const int step = gridDim.x * 8;
;     for (int row = opaque_bid() * 8 + wid; row < NOUTROWS; row += 2 * step) {
;         const int row2 = row + step; const bool has2 = row2 < NOUTROWS;
;         float* rp = p.out + (size_t)row * DM; float* rp2 = p.out + (size_t)(has2 ? row2 : row) * DM;
;         f32x4 v[8], v2[8];
; #pragma unroll
;         for (int it = 0; it < 8; ++it) v[it] = __builtin_nontemporal_load((const f32x4*)(rp + it * 256 + lane * 4));
; #pragma unroll
;         for (int it = 0; it < 8; ++it) v2[it] = __builtin_nontemporal_load((const f32x4*)(rp2 + it * 256 + lane * 4));
;         const float r = rsqrtf(SS3[row] * (1.f / 2048.f) + EPS), r2 = rsqrtf(SS3[has2 ? row2 : row] * (1.f / 2048.f) + EPS);
; #pragma unroll
;         for (int it = 0; it < 8; ++it) {
;             const int col = it * 256 + lane * 4;
;             const f32x4 w = *(const f32x4*)(nw + col);
;             __builtin_nontemporal_store(v[it] * r * w, (f32x4*)(rp + col));
;             if (has2) __builtin_nontemporal_store(v2[it] * r2 * w, (f32x4*)(rp2 + col));
.LBB0_860:
	s_nop 0
	v_readlane_b32 s0, v255, 33
	v_readlane_b32 s1, v255, 34
	s_and_b64 vcc, exec, s[0:1]
	s_cbranch_vccz .LBB0_881
	s_waitcnt vmcnt(0) lgkmcnt(0)
	v_readlane_b32 s0, v254, 0
	v_lshrrev_b32_e32 v4, 6, v151
	v_and_b32_e32 v5, 63, v151
	v_readlane_b32 s2, v255, 31
	v_readfirstlane_b32 s1, v4
	v_readlane_b32 s3, v255, 32
	v_readlane_b32 s4, v254, 37
	v_readlane_b32 s5, v254, 38
	s_and_b32 s6, s0, 0x7f
	s_lshl_b32 s6, s6, 3
	s_add_i32 s16, s6, s1
	v_lshlrev_b32_e32 v132, 4, v5
	v_add_u32_e32 v133, 0x1000, v132
	s_cmpk_lt_u32 s0, 0x80
	s_cselect_b32 s7, 0, 0xc00
	s_add_i32 s17, s16, s7
	s_lshl_b32 s6, s17, 13
	s_add_u32 s20, s2, s6
	s_addc_u32 s21, s3, 0
	s_lshl_b32 s6, s17, 2
	s_add_u32 s28, s82, 0x22b29400
	s_addc_u32 s29, s83, 0
	s_add_u32 s28, s28, s6
	s_addc_u32 s29, s29, 0
	s_cmpk_lt_u32 s0, 0x80
	s_cbranch_scc1 .Lp8_low
	s_add_u32 s22, s20, 0x800000
	s_addc_u32 s23, s21, 0
	s_add_u32 s24, s22, 0x800000
	s_addc_u32 s25, s23, 0
	s_add_u32 s26, s24, 0x800000
	s_addc_u32 s27, s25, 0
	s_add_u32 s30, s26, 0x800000
	s_addc_u32 s31, s27, 0
	global_load_dword v134, v149, s[28:29]
	s_add_u32 s28, s28, 0x1000
	s_addc_u32 s29, s29, 0
	global_load_dword v136, v149, s[28:29]
	s_add_u32 s28, s28, 0x1000
	s_addc_u32 s29, s29, 0
	global_load_dword v138, v149, s[28:29]
	s_add_u32 s28, s28, 0x1000
	s_addc_u32 s29, s29, 0
	global_load_dword v140, v149, s[28:29]
	s_add_u32 s28, s28, 0x1000
	s_addc_u32 s29, s29, 0
	global_load_dword v142, v149, s[28:29]
	global_load_dwordx4 v[170:173], v132, s[4:5]
	global_load_dwordx4 v[174:177], v132, s[4:5] offset:1024
	global_load_dwordx4 v[178:181], v132, s[4:5] offset:2048
	global_load_dwordx4 v[182:185], v132, s[4:5] offset:3072
	global_load_dwordx4 v[186:189], v133, s[4:5]
	global_load_dwordx4 v[190:193], v133, s[4:5] offset:1024
	global_load_dwordx4 v[194:197], v133, s[4:5] offset:2048
	global_load_dwordx4 v[198:201], v133, s[4:5] offset:3072
	global_load_dwordx4 v[4:7], v132, s[20:21] nt
	global_load_dwordx4 v[8:11], v132, s[20:21] offset:1024 nt
	global_load_dwordx4 v[12:15], v132, s[20:21] offset:2048 nt
	global_load_dwordx4 v[16:19], v132, s[20:21] offset:3072 nt
	global_load_dwordx4 v[20:23], v133, s[20:21] nt
	global_load_dwordx4 v[24:27], v133, s[20:21] offset:1024 nt
	global_load_dwordx4 v[28:31], v133, s[20:21] offset:2048 nt
	global_load_dwordx4 v[32:35], v133, s[20:21] offset:3072 nt
	global_load_dwordx4 v[36:39], v132, s[22:23] nt
	global_load_dwordx4 v[40:43], v132, s[22:23] offset:1024 nt
	global_load_dwordx4 v[44:47], v132, s[22:23] offset:2048 nt
	global_load_dwordx4 v[48:51], v132, s[22:23] offset:3072 nt
	global_load_dwordx4 v[52:55], v133, s[22:23] nt
	global_load_dwordx4 v[56:59], v133, s[22:23] offset:1024 nt
	global_load_dwordx4 v[60:63], v133, s[22:23] offset:2048 nt
	global_load_dwordx4 v[64:67], v133, s[22:23] offset:3072 nt
	global_load_dwordx4 v[68:71], v132, s[24:25] nt
	global_load_dwordx4 v[72:75], v132, s[24:25] offset:1024 nt
	global_load_dwordx4 v[76:79], v132, s[24:25] offset:2048 nt
	global_load_dwordx4 v[80:83], v132, s[24:25] offset:3072 nt
	global_load_dwordx4 v[84:87], v133, s[24:25] nt
	global_load_dwordx4 v[88:91], v133, s[24:25] offset:1024 nt
	global_load_dwordx4 v[92:95], v133, s[24:25] offset:2048 nt
	global_load_dwordx4 v[96:99], v133, s[24:25] offset:3072 nt
	global_load_dwordx4 v[100:103], v132, s[26:27] nt
	global_load_dwordx4 v[104:107], v132, s[26:27] offset:1024 nt
	global_load_dwordx4 v[108:111], v132, s[26:27] offset:2048 nt
	global_load_dwordx4 v[112:115], v132, s[26:27] offset:3072 nt
	global_load_dwordx4 v[116:119], v133, s[26:27] nt
	global_load_dwordx4 v[120:123], v133, s[26:27] offset:1024 nt
	global_load_dwordx4 v[124:127], v133, s[26:27] offset:2048 nt
	global_load_dwordx4 v[128:131], v133, s[26:27] offset:3072 nt
	global_load_dwordx4 v[214:217], v132, s[30:31] nt
	global_load_dwordx4 v[218:221], v132, s[30:31] offset:1024 nt
	global_load_dwordx4 v[222:225], v132, s[30:31] offset:2048 nt
	global_load_dwordx4 v[226:229], v132, s[30:31] offset:3072 nt
	global_load_dwordx4 v[230:233], v133, s[30:31] nt
	global_load_dwordx4 v[234:237], v133, s[30:31] offset:1024 nt
	global_load_dwordx4 v[238:241], v133, s[30:31] offset:2048 nt
	global_load_dwordx4 v[242:245], v133, s[30:31] offset:3072 nt
	s_waitcnt vmcnt(48)
	v_fmamk_f32 v134, v134, 0x3a000000, v202
	v_fmamk_f32 v136, v136, 0x3a000000, v202
	v_fmamk_f32 v138, v138, 0x3a000000, v202
	v_fmamk_f32 v140, v140, 0x3a000000, v202
	v_fmamk_f32 v142, v142, 0x3a000000, v202
	v_rsq_f32_e32 v134, v134
	v_rsq_f32_e32 v136, v136
	v_rsq_f32_e32 v138, v138
	v_rsq_f32_e32 v140, v140
	v_rsq_f32_e32 v142, v142
	s_waitcnt vmcnt(32)
; __device__ __forceinline__ void phase_final(const Params& p) {
;     ...
; #pragma unroll
;         for (int it = 0; it < 8; ++it) {
;             const int col = it * 256 + lane * 4;
;             const f32x4 w = *(const f32x4*)(nw + col);
;             __builtin_nontemporal_store(v[it] * r * w, (f32x4*)(rp + col));
;             if (has2) __builtin_nontemporal_store(v2[it] * r2 * w, (f32x4*)(rp2 + col));
;         }
	v_pk_mul_f32 v[4:5], v[4:5], v[134:135] op_sel_hi:[1,0]
	v_pk_mul_f32 v[6:7], v[6:7], v[134:135] op_sel_hi:[1,0]
	v_pk_mul_f32 v[4:5], v[4:5], v[170:171]
	v_pk_mul_f32 v[6:7], v[6:7], v[172:173]
	global_store_dwordx4 v132, v[4:7], s[20:21] nt
	v_pk_mul_f32 v[8:9], v[8:9], v[134:135] op_sel_hi:[1,0]
	v_pk_mul_f32 v[10:11], v[10:11], v[134:135] op_sel_hi:[1,0]
	v_pk_mul_f32 v[8:9], v[8:9], v[174:175]
	v_pk_mul_f32 v[10:11], v[10:11], v[176:177]
	global_store_dwordx4 v132, v[8:11], s[20:21] offset:1024 nt
	v_pk_mul_f32 v[12:13], v[12:13], v[134:135] op_sel_hi:[1,0]
	v_pk_mul_f32 v[14:15], v[14:15], v[134:135] op_sel_hi:[1,0]
	v_pk_mul_f32 v[12:13], v[12:13], v[178:179]
	v_pk_mul_f32 v[14:15], v[14:15], v[180:181]
	global_store_dwordx4 v132, v[12:15], s[20:21] offset:2048 nt
	v_pk_mul_f32 v[16:17], v[16:17], v[134:135] op_sel_hi:[1,0]
	v_pk_mul_f32 v[18:19], v[18:19], v[134:135] op_sel_hi:[1,0]
	v_pk_mul_f32 v[16:17], v[16:17], v[182:183]
	v_pk_mul_f32 v[18:19], v[18:19], v[184:185]
	global_store_dwordx4 v132, v[16:19], s[20:21] offset:3072 nt
	v_pk_mul_f32 v[20:21], v[20:21], v[134:135] op_sel_hi:[1,0]
	v_pk_mul_f32 v[22:23], v[22:23], v[134:135] op_sel_hi:[1,0]
	v_pk_mul_f32 v[20:21], v[20:21], v[186:187]
	v_pk_mul_f32 v[22:23], v[22:23], v[188:189]
	global_store_dwordx4 v133, v[20:23], s[20:21] nt
	v_pk_mul_f32 v[24:25], v[24:25], v[134:135] op_sel_hi:[1,0]
	v_pk_mul_f32 v[26:27], v[26:27], v[134:135] op_sel_hi:[1,0]
	v_pk_mul_f32 v[24:25], v[24:25], v[190:191]
	v_pk_mul_f32 v[26:27], v[26:27], v[192:193]
	global_store_dwordx4 v133, v[24:27], s[20:21] offset:1024 nt
	v_pk_mul_f32 v[28:29], v[28:29], v[134:135] op_sel_hi:[1,0]
	v_pk_mul_f32 v[30:31], v[30:31], v[134:135] op_sel_hi:[1,0]
	v_pk_mul_f32 v[28:29], v[28:29], v[194:195]
	v_pk_mul_f32 v[30:31], v[30:31], v[196:197]
	global_store_dwordx4 v133, v[28:31], s[20:21] offset:2048 nt
	v_pk_mul_f32 v[32:33], v[32:33], v[134:135] op_sel_hi:[1,0]
	v_pk_mul_f32 v[34:35], v[34:35], v[134:135] op_sel_hi:[1,0]
	v_pk_mul_f32 v[32:33], v[32:33], v[198:199]
	v_pk_mul_f32 v[34:35], v[34:35], v[200:201]
	global_store_dwordx4 v133, v[32:35], s[20:21] offset:3072 nt
	s_waitcnt vmcnt(32)
	v_pk_mul_f32 v[36:37], v[36:37], v[136:137] op_sel_hi:[1,0]
	v_pk_mul_f32 v[38:39], v[38:39], v[136:137] op_sel_hi:[1,0]
	v_pk_mul_f32 v[36:37], v[36:37], v[170:171]
	v_pk_mul_f32 v[38:39], v[38:39], v[172:173]
	global_store_dwordx4 v132, v[36:39], s[22:23] nt
	v_pk_mul_f32 v[40:41], v[40:41], v[136:137] op_sel_hi:[1,0]
	v_pk_mul_f32 v[42:43], v[42:43], v[136:137] op_sel_hi:[1,0]
	v_pk_mul_f32 v[40:41], v[40:41], v[174:175]
	v_pk_mul_f32 v[42:43], v[42:43], v[176:177]
	global_store_dwordx4 v132, v[40:43], s[22:23] offset:1024 nt
	v_pk_mul_f32 v[44:45], v[44:45], v[136:137] op_sel_hi:[1,0]
	v_pk_mul_f32 v[46:47], v[46:47], v[136:137] op_sel_hi:[1,0]
	v_pk_mul_f32 v[44:45], v[44:45], v[178:179]
	v_pk_mul_f32 v[46:47], v[46:47], v[180:181]
	global_store_dwordx4 v132, v[44:47], s[22:23] offset:2048 nt
	v_pk_mul_f32 v[48:49], v[48:49], v[136:137] op_sel_hi:[1,0]
	v_pk_mul_f32 v[50:51], v[50:51], v[136:137] op_sel_hi:[1,0]
	v_pk_mul_f32 v[48:49], v[48:49], v[182:183]
	v_pk_mul_f32 v[50:51], v[50:51], v[184:185]
	global_store_dwordx4 v132, v[48:51], s[22:23] offset:3072 nt
	v_pk_mul_f32 v[52:53], v[52:53], v[136:137] op_sel_hi:[1,0]
	v_pk_mul_f32 v[54:55], v[54:55], v[136:137] op_sel_hi:[1,0]
	v_pk_mul_f32 v[52:53], v[52:53], v[186:187]
	v_pk_mul_f32 v[54:55], v[54:55], v[188:189]
	global_store_dwordx4 v133, v[52:55], s[22:23] nt
	v_pk_mul_f32 v[56:57], v[56:57], v[136:137] op_sel_hi:[1,0]
	v_pk_mul_f32 v[58:59], v[58:59], v[136:137] op_sel_hi:[1,0]
	v_pk_mul_f32 v[56:57], v[56:57], v[190:191]
	v_pk_mul_f32 v[58:59], v[58:59], v[192:193]
	global_store_dwordx4 v133, v[56:59], s[22:23] offset:1024 nt
	v_pk_mul_f32 v[60:61], v[60:61], v[136:137] op_sel_hi:[1,0]
	v_pk_mul_f32 v[62:63], v[62:63], v[136:137] op_sel_hi:[1,0]
	v_pk_mul_f32 v[60:61], v[60:61], v[194:195]
	v_pk_mul_f32 v[62:63], v[62:63], v[196:197]
	global_store_dwordx4 v133, v[60:63], s[22:23] offset:2048 nt
	v_pk_mul_f32 v[64:65], v[64:65], v[136:137] op_sel_hi:[1,0]
	v_pk_mul_f32 v[66:67], v[66:67], v[136:137] op_sel_hi:[1,0]
	v_pk_mul_f32 v[64:65], v[64:65], v[198:199]
	v_pk_mul_f32 v[66:67], v[66:67], v[200:201]
	global_store_dwordx4 v133, v[64:67], s[22:23] offset:3072 nt
	s_waitcnt vmcnt(32)
	v_pk_mul_f32 v[68:69], v[68:69], v[138:139] op_sel_hi:[1,0]
	v_pk_mul_f32 v[70:71], v[70:71], v[138:139] op_sel_hi:[1,0]
	v_pk_mul_f32 v[68:69], v[68:69], v[170:171]
	v_pk_mul_f32 v[70:71], v[70:71], v[172:173]
	global_store_dwordx4 v132, v[68:71], s[24:25] nt
	v_pk_mul_f32 v[72:73], v[72:73], v[138:139] op_sel_hi:[1,0]
	v_pk_mul_f32 v[74:75], v[74:75], v[138:139] op_sel_hi:[1,0]
	v_pk_mul_f32 v[72:73], v[72:73], v[174:175]
	v_pk_mul_f32 v[74:75], v[74:75], v[176:177]
	global_store_dwordx4 v132, v[72:75], s[24:25] offset:1024 nt
	v_pk_mul_f32 v[76:77], v[76:77], v[138:139] op_sel_hi:[1,0]
	v_pk_mul_f32 v[78:79], v[78:79], v[138:139] op_sel_hi:[1,0]
	v_pk_mul_f32 v[76:77], v[76:77], v[178:179]
	v_pk_mul_f32 v[78:79], v[78:79], v[180:181]
	global_store_dwordx4 v132, v[76:79], s[24:25] offset:2048 nt
	v_pk_mul_f32 v[80:81], v[80:81], v[138:139] op_sel_hi:[1,0]
	v_pk_mul_f32 v[82:83], v[82:83], v[138:139] op_sel_hi:[1,0]
	v_pk_mul_f32 v[80:81], v[80:81], v[182:183]
	v_pk_mul_f32 v[82:83], v[82:83], v[184:185]
	global_store_dwordx4 v132, v[80:83], s[24:25] offset:3072 nt
	v_pk_mul_f32 v[84:85], v[84:85], v[138:139] op_sel_hi:[1,0]
	v_pk_mul_f32 v[86:87], v[86:87], v[138:139] op_sel_hi:[1,0]
	v_pk_mul_f32 v[84:85], v[84:85], v[186:187]
	v_pk_mul_f32 v[86:87], v[86:87], v[188:189]
	global_store_dwordx4 v133, v[84:87], s[24:25] nt
	v_pk_mul_f32 v[88:89], v[88:89], v[138:139] op_sel_hi:[1,0]
	v_pk_mul_f32 v[90:91], v[90:91], v[138:139] op_sel_hi:[1,0]
	v_pk_mul_f32 v[88:89], v[88:89], v[190:191]
	v_pk_mul_f32 v[90:91], v[90:91], v[192:193]
	global_store_dwordx4 v133, v[88:91], s[24:25] offset:1024 nt
	v_pk_mul_f32 v[92:93], v[92:93], v[138:139] op_sel_hi:[1,0]
	v_pk_mul_f32 v[94:95], v[94:95], v[138:139] op_sel_hi:[1,0]
	v_pk_mul_f32 v[92:93], v[92:93], v[194:195]
	v_pk_mul_f32 v[94:95], v[94:95], v[196:197]
	global_store_dwordx4 v133, v[92:95], s[24:25] offset:2048 nt
	v_pk_mul_f32 v[96:97], v[96:97], v[138:139] op_sel_hi:[1,0]
	v_pk_mul_f32 v[98:99], v[98:99], v[138:139] op_sel_hi:[1,0]
	v_pk_mul_f32 v[96:97], v[96:97], v[198:199]
	v_pk_mul_f32 v[98:99], v[98:99], v[200:201]
	global_store_dwordx4 v133, v[96:99], s[24:25] offset:3072 nt
	s_waitcnt vmcnt(32)
; __device__ __forceinline__ void phase_final(const Params& p) {
;     ...
; #pragma unroll
;         for (int it = 0; it < 8; ++it) {
;             const int col = it * 256 + lane * 4;
;             const f32x4 w = *(const f32x4*)(nw + col);
;             __builtin_nontemporal_store(v[it] * r * w, (f32x4*)(rp + col));
;             if (has2) __builtin_nontemporal_store(v2[it] * r2 * w, (f32x4*)(rp2 + col));
;         }
	v_pk_mul_f32 v[100:101], v[100:101], v[140:141] op_sel_hi:[1,0]
	v_pk_mul_f32 v[102:103], v[102:103], v[140:141] op_sel_hi:[1,0]
	v_pk_mul_f32 v[100:101], v[100:101], v[170:171]
	v_pk_mul_f32 v[102:103], v[102:103], v[172:173]
	global_store_dwordx4 v132, v[100:103], s[26:27] nt
	v_pk_mul_f32 v[104:105], v[104:105], v[140:141] op_sel_hi:[1,0]
	v_pk_mul_f32 v[106:107], v[106:107], v[140:141] op_sel_hi:[1,0]
	v_pk_mul_f32 v[104:105], v[104:105], v[174:175]
	v_pk_mul_f32 v[106:107], v[106:107], v[176:177]
	global_store_dwordx4 v132, v[104:107], s[26:27] offset:1024 nt
	v_pk_mul_f32 v[108:109], v[108:109], v[140:141] op_sel_hi:[1,0]
	v_pk_mul_f32 v[110:111], v[110:111], v[140:141] op_sel_hi:[1,0]
	v_pk_mul_f32 v[108:109], v[108:109], v[178:179]
	v_pk_mul_f32 v[110:111], v[110:111], v[180:181]
	global_store_dwordx4 v132, v[108:111], s[26:27] offset:2048 nt
	v_pk_mul_f32 v[112:113], v[112:113], v[140:141] op_sel_hi:[1,0]
	v_pk_mul_f32 v[114:115], v[114:115], v[140:141] op_sel_hi:[1,0]
	v_pk_mul_f32 v[112:113], v[112:113], v[182:183]
	v_pk_mul_f32 v[114:115], v[114:115], v[184:185]
	global_store_dwordx4 v132, v[112:115], s[26:27] offset:3072 nt
	v_pk_mul_f32 v[116:117], v[116:117], v[140:141] op_sel_hi:[1,0]
	v_pk_mul_f32 v[118:119], v[118:119], v[140:141] op_sel_hi:[1,0]
	v_pk_mul_f32 v[116:117], v[116:117], v[186:187]
	v_pk_mul_f32 v[118:119], v[118:119], v[188:189]
	global_store_dwordx4 v133, v[116:119], s[26:27] nt
	v_pk_mul_f32 v[120:121], v[120:121], v[140:141] op_sel_hi:[1,0]
	v_pk_mul_f32 v[122:123], v[122:123], v[140:141] op_sel_hi:[1,0]
	v_pk_mul_f32 v[120:121], v[120:121], v[190:191]
	v_pk_mul_f32 v[122:123], v[122:123], v[192:193]
	global_store_dwordx4 v133, v[120:123], s[26:27] offset:1024 nt
	v_pk_mul_f32 v[124:125], v[124:125], v[140:141] op_sel_hi:[1,0]
	v_pk_mul_f32 v[126:127], v[126:127], v[140:141] op_sel_hi:[1,0]
	v_pk_mul_f32 v[124:125], v[124:125], v[194:195]
	v_pk_mul_f32 v[126:127], v[126:127], v[196:197]
	global_store_dwordx4 v133, v[124:127], s[26:27] offset:2048 nt
	v_pk_mul_f32 v[128:129], v[128:129], v[140:141] op_sel_hi:[1,0]
	v_pk_mul_f32 v[130:131], v[130:131], v[140:141] op_sel_hi:[1,0]
	v_pk_mul_f32 v[128:129], v[128:129], v[198:199]
	v_pk_mul_f32 v[130:131], v[130:131], v[200:201]
	global_store_dwordx4 v133, v[128:131], s[26:27] offset:3072 nt
	s_waitcnt vmcnt(32)
	v_pk_mul_f32 v[214:215], v[214:215], v[142:143] op_sel_hi:[1,0]
	v_pk_mul_f32 v[216:217], v[216:217], v[142:143] op_sel_hi:[1,0]
	v_pk_mul_f32 v[214:215], v[214:215], v[170:171]
	v_pk_mul_f32 v[216:217], v[216:217], v[172:173]
	global_store_dwordx4 v132, v[214:217], s[30:31] nt
	v_pk_mul_f32 v[218:219], v[218:219], v[142:143] op_sel_hi:[1,0]
	v_pk_mul_f32 v[220:221], v[220:221], v[142:143] op_sel_hi:[1,0]
	v_pk_mul_f32 v[218:219], v[218:219], v[174:175]
	v_pk_mul_f32 v[220:221], v[220:221], v[176:177]
	global_store_dwordx4 v132, v[218:221], s[30:31] offset:1024 nt
	v_pk_mul_f32 v[222:223], v[222:223], v[142:143] op_sel_hi:[1,0]
	v_pk_mul_f32 v[224:225], v[224:225], v[142:143] op_sel_hi:[1,0]
	v_pk_mul_f32 v[222:223], v[222:223], v[178:179]
	v_pk_mul_f32 v[224:225], v[224:225], v[180:181]
	global_store_dwordx4 v132, v[222:225], s[30:31] offset:2048 nt
	v_pk_mul_f32 v[226:227], v[226:227], v[142:143] op_sel_hi:[1,0]
	v_pk_mul_f32 v[228:229], v[228:229], v[142:143] op_sel_hi:[1,0]
	v_pk_mul_f32 v[226:227], v[226:227], v[182:183]
	v_pk_mul_f32 v[228:229], v[228:229], v[184:185]
	global_store_dwordx4 v132, v[226:229], s[30:31] offset:3072 nt
	v_pk_mul_f32 v[230:231], v[230:231], v[142:143] op_sel_hi:[1,0]
	v_pk_mul_f32 v[232:233], v[232:233], v[142:143] op_sel_hi:[1,0]
	v_pk_mul_f32 v[230:231], v[230:231], v[186:187]
	v_pk_mul_f32 v[232:233], v[232:233], v[188:189]
	global_store_dwordx4 v133, v[230:233], s[30:31] nt
	v_pk_mul_f32 v[234:235], v[234:235], v[142:143] op_sel_hi:[1,0]
	v_pk_mul_f32 v[236:237], v[236:237], v[142:143] op_sel_hi:[1,0]
	v_pk_mul_f32 v[234:235], v[234:235], v[190:191]
	v_pk_mul_f32 v[236:237], v[236:237], v[192:193]
	global_store_dwordx4 v133, v[234:237], s[30:31] offset:1024 nt
	v_pk_mul_f32 v[238:239], v[238:239], v[142:143] op_sel_hi:[1,0]
	v_pk_mul_f32 v[240:241], v[240:241], v[142:143] op_sel_hi:[1,0]
	v_pk_mul_f32 v[238:239], v[238:239], v[194:195]
	v_pk_mul_f32 v[240:241], v[240:241], v[196:197]
	global_store_dwordx4 v133, v[238:241], s[30:31] offset:2048 nt
	v_pk_mul_f32 v[242:243], v[242:243], v[142:143] op_sel_hi:[1,0]
	v_pk_mul_f32 v[244:245], v[244:245], v[142:143] op_sel_hi:[1,0]
	v_pk_mul_f32 v[242:243], v[242:243], v[198:199]
	v_pk_mul_f32 v[244:245], v[244:245], v[200:201]
	global_store_dwordx4 v133, v[242:245], s[30:31] offset:3072 nt
	s_branch .Lp8_done
; __device__ __forceinline__ int opaque_tid() { int t = threadIdx.x; asm volatile("" : "+v"(t)); return t; }
; __device__ __forceinline__ int opaque_bid() { int t = blockIdx.x; asm volatile("" : "+s"(t)); return t; }
; __device__ __forceinline__ void phase_final(const Params& p) {
;     const int tid = opaque_tid(), wid = tid >> 6, lane = tid & 63;
;     const float* SS3 = (const float*)(p.ws + WS_SS3); const float* nw = p.in[26];
;     const int step = gridDim.x * 8;
;     for (int row = opaque_bid() * 8 + wid; row < NOUTROWS; row += 2 * step) {
;         const int row2 = row + step; const bool has2 = row2 < NOUTROWS;
;         float* rp = p.out + (size_t)row * DM; float* rp2 = p.out + (size_t)(has2 ? row2 : row) * DM;
;         f32x4 v[8], v2[8];
; #pragma unroll
;         for (int it = 0; it < 8; ++it) v[it] = __builtin_nontemporal_load((const f32x4*)(rp + it * 256 + lane * 4));
; #pragma unroll
;         for (int it = 0; it < 8; ++it) v2[it] = __builtin_nontemporal_load((const f32x4*)(rp2 + it * 256 + lane * 4));
;         const float r = rsqrtf(SS3[row] * (1.f / 2048.f) + EPS), r2 = rsqrtf(SS3[has2 ? row2 : row] * (1.f / 2048.f) + EPS);
; #pragma unroll
;         for (int it = 0; it < 8; ++it) {
;             const int col = it * 256 + lane * 4;
;             const f32x4 w = *(const f32x4*)(nw + col);
;             __builtin_nontemporal_store(v[it] * r * w, (f32x4*)(rp + col));
;             if (has2) __builtin_nontemporal_store(v2[it] * r2 * w, (f32x4*)(rp2 + col));
.Lp8_low:
	s_add_u32 s22, s20, 0x800000
	s_addc_u32 s23, s21, 0
	s_add_u32 s24, s22, 0x800000
	s_addc_u32 s25, s23, 0
	global_load_dword v134, v149, s[28:29]
	s_add_u32 s28, s28, 0x1000
	s_addc_u32 s29, s29, 0
	global_load_dword v136, v149, s[28:29]
	s_add_u32 s28, s28, 0x1000
	s_addc_u32 s29, s29, 0
	global_load_dword v138, v149, s[28:29]
	global_load_dwordx4 v[170:173], v132, s[4:5]
	global_load_dwordx4 v[174:177], v132, s[4:5] offset:1024
	global_load_dwordx4 v[178:181], v132, s[4:5] offset:2048
	global_load_dwordx4 v[182:185], v132, s[4:5] offset:3072
	global_load_dwordx4 v[186:189], v133, s[4:5]
	global_load_dwordx4 v[190:193], v133, s[4:5] offset:1024
	global_load_dwordx4 v[194:197], v133, s[4:5] offset:2048
	global_load_dwordx4 v[198:201], v133, s[4:5] offset:3072
	global_load_dwordx4 v[4:7], v132, s[20:21] nt
	global_load_dwordx4 v[8:11], v132, s[20:21] offset:1024 nt
	global_load_dwordx4 v[12:15], v132, s[20:21] offset:2048 nt
	global_load_dwordx4 v[16:19], v132, s[20:21] offset:3072 nt
	global_load_dwordx4 v[20:23], v133, s[20:21] nt
	global_load_dwordx4 v[24:27], v133, s[20:21] offset:1024 nt
	global_load_dwordx4 v[28:31], v133, s[20:21] offset:2048 nt
	global_load_dwordx4 v[32:35], v133, s[20:21] offset:3072 nt
	global_load_dwordx4 v[36:39], v132, s[22:23] nt
	global_load_dwordx4 v[40:43], v132, s[22:23] offset:1024 nt
	global_load_dwordx4 v[44:47], v132, s[22:23] offset:2048 nt
	global_load_dwordx4 v[48:51], v132, s[22:23] offset:3072 nt
	global_load_dwordx4 v[52:55], v133, s[22:23] nt
	global_load_dwordx4 v[56:59], v133, s[22:23] offset:1024 nt
	global_load_dwordx4 v[60:63], v133, s[22:23] offset:2048 nt
	global_load_dwordx4 v[64:67], v133, s[22:23] offset:3072 nt
	global_load_dwordx4 v[68:71], v132, s[24:25] nt
	global_load_dwordx4 v[72:75], v132, s[24:25] offset:1024 nt
	global_load_dwordx4 v[76:79], v132, s[24:25] offset:2048 nt
	global_load_dwordx4 v[80:83], v132, s[24:25] offset:3072 nt
	global_load_dwordx4 v[84:87], v133, s[24:25] nt
	global_load_dwordx4 v[88:91], v133, s[24:25] offset:1024 nt
	global_load_dwordx4 v[92:95], v133, s[24:25] offset:2048 nt
	global_load_dwordx4 v[96:99], v133, s[24:25] offset:3072 nt
	s_waitcnt vmcnt(32)
	v_fmamk_f32 v134, v134, 0x3a000000, v202
	v_fmamk_f32 v136, v136, 0x3a000000, v202
	v_fmamk_f32 v138, v138, 0x3a000000, v202
	v_rsq_f32_e32 v134, v134
	v_rsq_f32_e32 v136, v136
	v_rsq_f32_e32 v138, v138
	s_waitcnt vmcnt(16)
	v_pk_mul_f32 v[4:5], v[4:5], v[134:135] op_sel_hi:[1,0]
	v_pk_mul_f32 v[6:7], v[6:7], v[134:135] op_sel_hi:[1,0]
	v_pk_mul_f32 v[4:5], v[4:5], v[170:171]
	v_pk_mul_f32 v[6:7], v[6:7], v[172:173]
	global_store_dwordx4 v132, v[4:7], s[20:21] nt
	v_pk_mul_f32 v[8:9], v[8:9], v[134:135] op_sel_hi:[1,0]
	v_pk_mul_f32 v[10:11], v[10:11], v[134:135] op_sel_hi:[1,0]
	v_pk_mul_f32 v[8:9], v[8:9], v[174:175]
	v_pk_mul_f32 v[10:11], v[10:11], v[176:177]
	global_store_dwordx4 v132, v[8:11], s[20:21] offset:1024 nt
	v_pk_mul_f32 v[12:13], v[12:13], v[134:135] op_sel_hi:[1,0]
	v_pk_mul_f32 v[14:15], v[14:15], v[134:135] op_sel_hi:[1,0]
	v_pk_mul_f32 v[12:13], v[12:13], v[178:179]
	v_pk_mul_f32 v[14:15], v[14:15], v[180:181]
	global_store_dwordx4 v132, v[12:15], s[20:21] offset:2048 nt
	v_pk_mul_f32 v[16:17], v[16:17], v[134:135] op_sel_hi:[1,0]
	v_pk_mul_f32 v[18:19], v[18:19], v[134:135] op_sel_hi:[1,0]
	v_pk_mul_f32 v[16:17], v[16:17], v[182:183]
	v_pk_mul_f32 v[18:19], v[18:19], v[184:185]
	global_store_dwordx4 v132, v[16:19], s[20:21] offset:3072 nt
	v_pk_mul_f32 v[20:21], v[20:21], v[134:135] op_sel_hi:[1,0]
	v_pk_mul_f32 v[22:23], v[22:23], v[134:135] op_sel_hi:[1,0]
	v_pk_mul_f32 v[20:21], v[20:21], v[186:187]
	v_pk_mul_f32 v[22:23], v[22:23], v[188:189]
	global_store_dwordx4 v133, v[20:23], s[20:21] nt
	v_pk_mul_f32 v[24:25], v[24:25], v[134:135] op_sel_hi:[1,0]
	v_pk_mul_f32 v[26:27], v[26:27], v[134:135] op_sel_hi:[1,0]
	v_pk_mul_f32 v[24:25], v[24:25], v[190:191]
	v_pk_mul_f32 v[26:27], v[26:27], v[192:193]
	global_store_dwordx4 v133, v[24:27], s[20:21] offset:1024 nt
	v_pk_mul_f32 v[28:29], v[28:29], v[134:135] op_sel_hi:[1,0]
	v_pk_mul_f32 v[30:31], v[30:31], v[134:135] op_sel_hi:[1,0]
	v_pk_mul_f32 v[28:29], v[28:29], v[194:195]
	v_pk_mul_f32 v[30:31], v[30:31], v[196:197]
	global_store_dwordx4 v133, v[28:31], s[20:21] offset:2048 nt
	v_pk_mul_f32 v[32:33], v[32:33], v[134:135] op_sel_hi:[1,0]
	v_pk_mul_f32 v[34:35], v[34:35], v[134:135] op_sel_hi:[1,0]
	v_pk_mul_f32 v[32:33], v[32:33], v[198:199]
	v_pk_mul_f32 v[34:35], v[34:35], v[200:201]
	global_store_dwordx4 v133, v[32:35], s[20:21] offset:3072 nt
	s_waitcnt vmcnt(16)
;     __device__ __forceinline__ void operator()(const AccT& acc, const pg8::Unit& u, int wr, int wc, int fr, int fq) const {
;     ...
;                         const f32x4 v0 = acc[ai][bj][m][0] + __builtin_nontemporal_load((const f32x4*)(H1 + (size_t)row * DM + col0 + bj * 128));
;                         const f32x4 v1 = acc[ai][bj][m][1] + __builtin_nontemporal_load((const f32x4*)(H1 + (size_t)row * DM + col0 + bj * 128 + 4));
; __device__ __forceinline__ void phase_final(const Params& p) {
;     ...
; #pragma unroll
;         for (int it = 0; it < 8; ++it) {
;             const int col = it * 256 + lane * 4;
;             const f32x4 w = *(const f32x4*)(nw + col);
;             __builtin_nontemporal_store(v[it] * r * w, (f32x4*)(rp + col));
;             if (has2) __builtin_nontemporal_store(v2[it] * r2 * w, (f32x4*)(rp2 + col));
;         }
	v_pk_mul_f32 v[36:37], v[36:37], v[136:137] op_sel_hi:[1,0]
	v_pk_mul_f32 v[38:39], v[38:39], v[136:137] op_sel_hi:[1,0]
	v_pk_mul_f32 v[36:37], v[36:37], v[170:171]
	v_pk_mul_f32 v[38:39], v[38:39], v[172:173]
	global_store_dwordx4 v132, v[36:39], s[22:23] nt
	v_pk_mul_f32 v[40:41], v[40:41], v[136:137] op_sel_hi:[1,0]
	v_pk_mul_f32 v[42:43], v[42:43], v[136:137] op_sel_hi:[1,0]
	v_pk_mul_f32 v[40:41], v[40:41], v[174:175]
	v_pk_mul_f32 v[42:43], v[42:43], v[176:177]
	global_store_dwordx4 v132, v[40:43], s[22:23] offset:1024 nt
	v_pk_mul_f32 v[44:45], v[44:45], v[136:137] op_sel_hi:[1,0]
	v_pk_mul_f32 v[46:47], v[46:47], v[136:137] op_sel_hi:[1,0]
	v_pk_mul_f32 v[44:45], v[44:45], v[178:179]
	v_pk_mul_f32 v[46:47], v[46:47], v[180:181]
	global_store_dwordx4 v132, v[44:47], s[22:23] offset:2048 nt
	v_pk_mul_f32 v[48:49], v[48:49], v[136:137] op_sel_hi:[1,0]
	v_pk_mul_f32 v[50:51], v[50:51], v[136:137] op_sel_hi:[1,0]
	v_pk_mul_f32 v[48:49], v[48:49], v[182:183]
	v_pk_mul_f32 v[50:51], v[50:51], v[184:185]
	global_store_dwordx4 v132, v[48:51], s[22:23] offset:3072 nt
	v_pk_mul_f32 v[52:53], v[52:53], v[136:137] op_sel_hi:[1,0]
	v_pk_mul_f32 v[54:55], v[54:55], v[136:137] op_sel_hi:[1,0]
	v_pk_mul_f32 v[52:53], v[52:53], v[186:187]
	v_pk_mul_f32 v[54:55], v[54:55], v[188:189]
	global_store_dwordx4 v133, v[52:55], s[22:23] nt
	v_pk_mul_f32 v[56:57], v[56:57], v[136:137] op_sel_hi:[1,0]
	v_pk_mul_f32 v[58:59], v[58:59], v[136:137] op_sel_hi:[1,0]
	v_pk_mul_f32 v[56:57], v[56:57], v[190:191]
	v_pk_mul_f32 v[58:59], v[58:59], v[192:193]
	global_store_dwordx4 v133, v[56:59], s[22:23] offset:1024 nt
	v_pk_mul_f32 v[60:61], v[60:61], v[136:137] op_sel_hi:[1,0]
	v_pk_mul_f32 v[62:63], v[62:63], v[136:137] op_sel_hi:[1,0]
	v_pk_mul_f32 v[60:61], v[60:61], v[194:195]
	v_pk_mul_f32 v[62:63], v[62:63], v[196:197]
	global_store_dwordx4 v133, v[60:63], s[22:23] offset:2048 nt
	v_pk_mul_f32 v[64:65], v[64:65], v[136:137] op_sel_hi:[1,0]
	v_pk_mul_f32 v[66:67], v[66:67], v[136:137] op_sel_hi:[1,0]
	v_pk_mul_f32 v[64:65], v[64:65], v[198:199]
	v_pk_mul_f32 v[66:67], v[66:67], v[200:201]
	global_store_dwordx4 v133, v[64:67], s[22:23] offset:3072 nt
	s_waitcnt vmcnt(16)
	v_pk_mul_f32 v[68:69], v[68:69], v[138:139] op_sel_hi:[1,0]
	v_pk_mul_f32 v[70:71], v[70:71], v[138:139] op_sel_hi:[1,0]
	v_pk_mul_f32 v[68:69], v[68:69], v[170:171]
	v_pk_mul_f32 v[70:71], v[70:71], v[172:173]
	global_store_dwordx4 v132, v[68:71], s[24:25] nt
	v_pk_mul_f32 v[72:73], v[72:73], v[138:139] op_sel_hi:[1,0]
	v_pk_mul_f32 v[74:75], v[74:75], v[138:139] op_sel_hi:[1,0]
	v_pk_mul_f32 v[72:73], v[72:73], v[174:175]
	v_pk_mul_f32 v[74:75], v[74:75], v[176:177]
	global_store_dwordx4 v132, v[72:75], s[24:25] offset:1024 nt
	v_pk_mul_f32 v[76:77], v[76:77], v[138:139] op_sel_hi:[1,0]
	v_pk_mul_f32 v[78:79], v[78:79], v[138:139] op_sel_hi:[1,0]
	v_pk_mul_f32 v[76:77], v[76:77], v[178:179]
	v_pk_mul_f32 v[78:79], v[78:79], v[180:181]
	global_store_dwordx4 v132, v[76:79], s[24:25] offset:2048 nt
	v_pk_mul_f32 v[80:81], v[80:81], v[138:139] op_sel_hi:[1,0]
	v_pk_mul_f32 v[82:83], v[82:83], v[138:139] op_sel_hi:[1,0]
	v_pk_mul_f32 v[80:81], v[80:81], v[182:183]
	v_pk_mul_f32 v[82:83], v[82:83], v[184:185]
	global_store_dwordx4 v132, v[80:83], s[24:25] offset:3072 nt
	v_pk_mul_f32 v[84:85], v[84:85], v[138:139] op_sel_hi:[1,0]
	v_pk_mul_f32 v[86:87], v[86:87], v[138:139] op_sel_hi:[1,0]
	v_pk_mul_f32 v[84:85], v[84:85], v[186:187]
	v_pk_mul_f32 v[86:87], v[86:87], v[188:189]
	global_store_dwordx4 v133, v[84:87], s[24:25] nt
	v_pk_mul_f32 v[88:89], v[88:89], v[138:139] op_sel_hi:[1,0]
	v_pk_mul_f32 v[90:91], v[90:91], v[138:139] op_sel_hi:[1,0]
	v_pk_mul_f32 v[88:89], v[88:89], v[190:191]
	v_pk_mul_f32 v[90:91], v[90:91], v[192:193]
	global_store_dwordx4 v133, v[88:91], s[24:25] offset:1024 nt
	v_pk_mul_f32 v[92:93], v[92:93], v[138:139] op_sel_hi:[1,0]
	v_pk_mul_f32 v[94:95], v[94:95], v[138:139] op_sel_hi:[1,0]
	v_pk_mul_f32 v[92:93], v[92:93], v[194:195]
	v_pk_mul_f32 v[94:95], v[94:95], v[196:197]
	global_store_dwordx4 v133, v[92:95], s[24:25] offset:2048 nt
	v_pk_mul_f32 v[96:97], v[96:97], v[138:139] op_sel_hi:[1,0]
	v_pk_mul_f32 v[98:99], v[98:99], v[138:139] op_sel_hi:[1,0]
	v_pk_mul_f32 v[96:97], v[96:97], v[198:199]
	v_pk_mul_f32 v[98:99], v[98:99], v[200:201]
	global_store_dwordx4 v133, v[96:99], s[24:25] offset:3072 nt
	s_lshl_b32 s6, s16, 13
	s_add_u32 s8, s82, 0x1f780000
	s_addc_u32 s9, s83, 0
	s_add_u32 s8, s8, s6
	s_addc_u32 s9, s9, 0
	s_add_u32 s10, s82, 0xec00000
	s_addc_u32 s11, s83, 0
	s_add_u32 s10, s10, s6
	s_addc_u32 s11, s11, 0
	s_add_u32 s12, s10, 0x800000
	s_addc_u32 s13, s11, 0
	s_add_u32 s14, s12, 0x800000
	s_addc_u32 s15, s13, 0
	s_add_u32 s18, s14, 0x800000
	s_addc_u32 s19, s15, 0
	s_add_u32 s20, s2, s6
	s_addc_u32 s21, s3, 0
	s_add_u32 s20, s20, 0x4000000
	s_addc_u32 s21, s21, 0
	global_load_dwordx4 v[4:7], v132, s[8:9] nt
	global_load_dwordx4 v[8:11], v132, s[8:9] offset:1024 nt
	global_load_dwordx4 v[12:15], v132, s[8:9] offset:2048 nt
	global_load_dwordx4 v[16:19], v132, s[8:9] offset:3072 nt
	global_load_dwordx4 v[20:23], v133, s[8:9] nt
	global_load_dwordx4 v[24:27], v133, s[8:9] offset:1024 nt
	global_load_dwordx4 v[28:31], v133, s[8:9] offset:2048 nt
	global_load_dwordx4 v[32:35], v133, s[8:9] offset:3072 nt
	global_load_dwordx4 v[36:39], v132, s[10:11] nt
	global_load_dwordx4 v[40:43], v132, s[10:11] offset:1024 nt
	global_load_dwordx4 v[44:47], v132, s[10:11] offset:2048 nt
	global_load_dwordx4 v[48:51], v132, s[10:11] offset:3072 nt
	global_load_dwordx4 v[52:55], v133, s[10:11] nt
	global_load_dwordx4 v[56:59], v133, s[10:11] offset:1024 nt
;     __device__ __forceinline__ void operator()(const AccT& acc, const pg8::Unit& u, int wr, int wc, int fr, int fq) const {
;     ...
;                         const f32x4 v0 = acc[ai][bj][m][0] + __builtin_nontemporal_load((const f32x4*)(H1 + (size_t)row * DM + col0 + bj * 128));
;                         const f32x4 v1 = acc[ai][bj][m][1] + __builtin_nontemporal_load((const f32x4*)(H1 + (size_t)row * DM + col0 + bj * 128 + 4));
	global_load_dwordx4 v[60:63], v133, s[10:11] offset:2048 nt
	global_load_dwordx4 v[64:67], v133, s[10:11] offset:3072 nt
	global_load_dwordx4 v[68:71], v132, s[12:13] nt
	global_load_dwordx4 v[72:75], v132, s[12:13] offset:1024 nt
	global_load_dwordx4 v[76:79], v132, s[12:13] offset:2048 nt
	global_load_dwordx4 v[80:83], v132, s[12:13] offset:3072 nt
	global_load_dwordx4 v[84:87], v133, s[12:13] nt
	global_load_dwordx4 v[88:91], v133, s[12:13] offset:1024 nt
	global_load_dwordx4 v[92:95], v133, s[12:13] offset:2048 nt
	global_load_dwordx4 v[96:99], v133, s[12:13] offset:3072 nt
	global_load_dwordx4 v[100:103], v132, s[14:15] nt
	global_load_dwordx4 v[104:107], v132, s[14:15] offset:1024 nt
	global_load_dwordx4 v[108:111], v132, s[14:15] offset:2048 nt
	global_load_dwordx4 v[112:115], v132, s[14:15] offset:3072 nt
	global_load_dwordx4 v[116:119], v133, s[14:15] nt
	global_load_dwordx4 v[120:123], v133, s[14:15] offset:1024 nt
	global_load_dwordx4 v[124:127], v133, s[14:15] offset:2048 nt
	global_load_dwordx4 v[128:131], v133, s[14:15] offset:3072 nt
	global_load_dwordx4 v[214:217], v132, s[18:19] nt
	global_load_dwordx4 v[218:221], v132, s[18:19] offset:1024 nt
	global_load_dwordx4 v[222:225], v132, s[18:19] offset:2048 nt
	global_load_dwordx4 v[226:229], v132, s[18:19] offset:3072 nt
	global_load_dwordx4 v[230:233], v133, s[18:19] nt
	global_load_dwordx4 v[234:237], v133, s[18:19] offset:1024 nt
	global_load_dwordx4 v[238:241], v133, s[18:19] offset:2048 nt
	global_load_dwordx4 v[242:245], v133, s[18:19] offset:3072 nt
	s_waitcnt vmcnt(24)
	v_pk_add_f32 v[4:5], v[4:5], v[36:37]
	v_pk_add_f32 v[6:7], v[6:7], v[38:39]
	v_pk_add_f32 v[8:9], v[8:9], v[40:41]
	v_pk_add_f32 v[10:11], v[10:11], v[42:43]
	v_pk_add_f32 v[12:13], v[12:13], v[44:45]
	v_pk_add_f32 v[14:15], v[14:15], v[46:47]
	v_pk_add_f32 v[16:17], v[16:17], v[48:49]
	v_pk_add_f32 v[18:19], v[18:19], v[50:51]
	v_pk_add_f32 v[20:21], v[20:21], v[52:53]
	v_pk_add_f32 v[22:23], v[22:23], v[54:55]
	v_pk_add_f32 v[24:25], v[24:25], v[56:57]
	v_pk_add_f32 v[26:27], v[26:27], v[58:59]
	v_pk_add_f32 v[28:29], v[28:29], v[60:61]
	v_pk_add_f32 v[30:31], v[30:31], v[62:63]
	v_pk_add_f32 v[32:33], v[32:33], v[64:65]
	v_pk_add_f32 v[34:35], v[34:35], v[66:67]
	s_waitcnt vmcnt(16)
	v_pk_add_f32 v[4:5], v[4:5], v[68:69]
	v_pk_add_f32 v[6:7], v[6:7], v[70:71]
	v_pk_add_f32 v[8:9], v[8:9], v[72:73]
	v_pk_add_f32 v[10:11], v[10:11], v[74:75]
	v_pk_add_f32 v[12:13], v[12:13], v[76:77]
	v_pk_add_f32 v[14:15], v[14:15], v[78:79]
	v_pk_add_f32 v[16:17], v[16:17], v[80:81]
	v_pk_add_f32 v[18:19], v[18:19], v[82:83]
	v_pk_add_f32 v[20:21], v[20:21], v[84:85]
	v_pk_add_f32 v[22:23], v[22:23], v[86:87]
	v_pk_add_f32 v[24:25], v[24:25], v[88:89]
	v_pk_add_f32 v[26:27], v[26:27], v[90:91]
	v_pk_add_f32 v[28:29], v[28:29], v[92:93]
	v_pk_add_f32 v[30:31], v[30:31], v[94:95]
	v_pk_add_f32 v[32:33], v[32:33], v[96:97]
	v_pk_add_f32 v[34:35], v[34:35], v[98:99]
	s_waitcnt vmcnt(8)
	v_pk_add_f32 v[4:5], v[4:5], v[100:101]
	v_pk_add_f32 v[6:7], v[6:7], v[102:103]
	v_pk_add_f32 v[8:9], v[8:9], v[104:105]
	v_pk_add_f32 v[10:11], v[10:11], v[106:107]
	v_pk_add_f32 v[12:13], v[12:13], v[108:109]
	v_pk_add_f32 v[14:15], v[14:15], v[110:111]
	v_pk_add_f32 v[16:17], v[16:17], v[112:113]
	v_pk_add_f32 v[18:19], v[18:19], v[114:115]
	v_pk_add_f32 v[20:21], v[20:21], v[116:117]
	v_pk_add_f32 v[22:23], v[22:23], v[118:119]
	v_pk_add_f32 v[24:25], v[24:25], v[120:121]
	v_pk_add_f32 v[26:27], v[26:27], v[122:123]
	v_pk_add_f32 v[28:29], v[28:29], v[124:125]
	v_pk_add_f32 v[30:31], v[30:31], v[126:127]
	v_pk_add_f32 v[32:33], v[32:33], v[128:129]
	v_pk_add_f32 v[34:35], v[34:35], v[130:131]
	s_waitcnt vmcnt(0)
;     __device__ __forceinline__ void operator()(const AccT& acc, const pg8::Unit& u, int wr, int wc, int fr, int fq) const {
;     ...
;                         ss += v0[0] * v0[0] + v0[1] * v0[1] + v0[2] * v0[2] + v0[3] * v0[3] + v1[0] * v1[0] + v1[1] * v1[1] + v1[2] * v1[2] + v1[3] * v1[3];
;                     }
;                     ss += __shfl_xor(ss, 16); ss += __shfl_xor(ss, 32);
; __device__ __forceinline__ void phase_final(const Params& p) {
;     ...
;         const float r = rsqrtf(SS3[row] * (1.f / 2048.f) + EPS), r2 = rsqrtf(SS3[has2 ? row2 : row] * (1.f / 2048.f) + EPS);
; #pragma unroll
;         for (int it = 0; it < 8; ++it) {
;             const int col = it * 256 + lane * 4;
;             const f32x4 w = *(const f32x4*)(nw + col);
;             __builtin_nontemporal_store(v[it] * r * w, (f32x4*)(rp + col));
;             if (has2) __builtin_nontemporal_store(v2[it] * r2 * w, (f32x4*)(rp2 + col));
;         }
	v_pk_add_f32 v[4:5], v[4:5], v[214:215]
	v_pk_add_f32 v[6:7], v[6:7], v[216:217]
	v_pk_add_f32 v[8:9], v[8:9], v[218:219]
	v_pk_add_f32 v[10:11], v[10:11], v[220:221]
	v_pk_add_f32 v[12:13], v[12:13], v[222:223]
	v_pk_add_f32 v[14:15], v[14:15], v[224:225]
	v_pk_add_f32 v[16:17], v[16:17], v[226:227]
	v_pk_add_f32 v[18:19], v[18:19], v[228:229]
	v_pk_add_f32 v[20:21], v[20:21], v[230:231]
	v_pk_add_f32 v[22:23], v[22:23], v[232:233]
	v_pk_add_f32 v[24:25], v[24:25], v[234:235]
	v_pk_add_f32 v[26:27], v[26:27], v[236:237]
	v_pk_add_f32 v[28:29], v[28:29], v[238:239]
	v_pk_add_f32 v[30:31], v[30:31], v[240:241]
	v_pk_add_f32 v[32:33], v[32:33], v[242:243]
	v_pk_add_f32 v[34:35], v[34:35], v[244:245]
	v_mul_f32_e32 v246, v4, v4
	v_mul_f32_e32 v247, v5, v5
	v_fmac_f32_e32 v246, v6, v6
	v_fmac_f32_e32 v247, v7, v7
	v_fmac_f32_e32 v246, v8, v8
	v_fmac_f32_e32 v247, v9, v9
	v_fmac_f32_e32 v246, v10, v10
	v_fmac_f32_e32 v247, v11, v11
	v_fmac_f32_e32 v246, v12, v12
	v_fmac_f32_e32 v247, v13, v13
	v_fmac_f32_e32 v246, v14, v14
	v_fmac_f32_e32 v247, v15, v15
	v_fmac_f32_e32 v246, v16, v16
	v_fmac_f32_e32 v247, v17, v17
	v_fmac_f32_e32 v246, v18, v18
	v_fmac_f32_e32 v247, v19, v19
	v_fmac_f32_e32 v246, v20, v20
	v_fmac_f32_e32 v247, v21, v21
	v_fmac_f32_e32 v246, v22, v22
	v_fmac_f32_e32 v247, v23, v23
	v_fmac_f32_e32 v246, v24, v24
	v_fmac_f32_e32 v247, v25, v25
	v_fmac_f32_e32 v246, v26, v26
	v_fmac_f32_e32 v247, v27, v27
	v_fmac_f32_e32 v246, v28, v28
	v_fmac_f32_e32 v247, v29, v29
	v_fmac_f32_e32 v246, v30, v30
	v_fmac_f32_e32 v247, v31, v31
	v_fmac_f32_e32 v246, v32, v32
	v_fmac_f32_e32 v247, v33, v33
	v_fmac_f32_e32 v246, v34, v34
	v_fmac_f32_e32 v247, v35, v35
	v_add_f32_e32 v246, v246, v247
	s_nop 1
	v_add_f32_dpp v246, v246, v246 quad_perm:[1,0,3,2] row_mask:0xf bank_mask:0xf
	s_nop 1
	v_add_f32_dpp v246, v246, v246 quad_perm:[2,3,0,1] row_mask:0xf bank_mask:0xf
	s_nop 1
	v_add_f32_dpp v246, v246, v246 row_half_mirror row_mask:0xf bank_mask:0xf
	s_nop 1
	v_add_f32_dpp v246, v246, v246 row_mirror row_mask:0xf bank_mask:0xf
	s_nop 1
	v_readlane_b32 s6, v246, 0
	v_readlane_b32 s7, v246, 16
	v_readlane_b32 s8, v246, 32
	v_readlane_b32 s9, v246, 48
	s_nop 1
	v_mov_b32_e32 v134, s6
	v_add_f32_e32 v134, s7, v134
	v_add_f32_e32 v134, s8, v134
	v_add_f32_e32 v134, s9, v134
	v_fmamk_f32 v134, v134, 0x3a000000, v202
	v_rsq_f32_e32 v134, v134
	s_nop 0
	v_pk_mul_f32 v[4:5], v[4:5], v[134:135] op_sel_hi:[1,0]
	v_pk_mul_f32 v[6:7], v[6:7], v[134:135] op_sel_hi:[1,0]
	v_pk_mul_f32 v[4:5], v[4:5], v[170:171]
	v_pk_mul_f32 v[6:7], v[6:7], v[172:173]
	global_store_dwordx4 v132, v[4:7], s[20:21] nt
	v_pk_mul_f32 v[8:9], v[8:9], v[134:135] op_sel_hi:[1,0]
	v_pk_mul_f32 v[10:11], v[10:11], v[134:135] op_sel_hi:[1,0]
	v_pk_mul_f32 v[8:9], v[8:9], v[174:175]
	v_pk_mul_f32 v[10:11], v[10:11], v[176:177]
	global_store_dwordx4 v132, v[8:11], s[20:21] offset:1024 nt
	v_pk_mul_f32 v[12:13], v[12:13], v[134:135] op_sel_hi:[1,0]
	v_pk_mul_f32 v[14:15], v[14:15], v[134:135] op_sel_hi:[1,0]
	v_pk_mul_f32 v[12:13], v[12:13], v[178:179]
	v_pk_mul_f32 v[14:15], v[14:15], v[180:181]
	global_store_dwordx4 v132, v[12:15], s[20:21] offset:2048 nt
	v_pk_mul_f32 v[16:17], v[16:17], v[134:135] op_sel_hi:[1,0]
	v_pk_mul_f32 v[18:19], v[18:19], v[134:135] op_sel_hi:[1,0]
	v_pk_mul_f32 v[16:17], v[16:17], v[182:183]
	v_pk_mul_f32 v[18:19], v[18:19], v[184:185]
	global_store_dwordx4 v132, v[16:19], s[20:21] offset:3072 nt
	v_pk_mul_f32 v[20:21], v[20:21], v[134:135] op_sel_hi:[1,0]
	v_pk_mul_f32 v[22:23], v[22:23], v[134:135] op_sel_hi:[1,0]
	v_pk_mul_f32 v[20:21], v[20:21], v[186:187]
	v_pk_mul_f32 v[22:23], v[22:23], v[188:189]
	global_store_dwordx4 v133, v[20:23], s[20:21] nt
	v_pk_mul_f32 v[24:25], v[24:25], v[134:135] op_sel_hi:[1,0]
	v_pk_mul_f32 v[26:27], v[26:27], v[134:135] op_sel_hi:[1,0]
	v_pk_mul_f32 v[24:25], v[24:25], v[190:191]
	v_pk_mul_f32 v[26:27], v[26:27], v[192:193]
	global_store_dwordx4 v133, v[24:27], s[20:21] offset:1024 nt
	v_pk_mul_f32 v[28:29], v[28:29], v[134:135] op_sel_hi:[1,0]
	v_pk_mul_f32 v[30:31], v[30:31], v[134:135] op_sel_hi:[1,0]
	v_pk_mul_f32 v[28:29], v[28:29], v[194:195]
	v_pk_mul_f32 v[30:31], v[30:31], v[196:197]
	global_store_dwordx4 v133, v[28:31], s[20:21] offset:2048 nt
	v_pk_mul_f32 v[32:33], v[32:33], v[134:135] op_sel_hi:[1,0]
	v_pk_mul_f32 v[34:35], v[34:35], v[134:135] op_sel_hi:[1,0]
	v_pk_mul_f32 v[32:33], v[32:33], v[198:199]
	v_pk_mul_f32 v[34:35], v[34:35], v[200:201]
	global_store_dwordx4 v133, v[32:35], s[20:21] offset:3072 nt
